# attention unit loop rewritten (all K/V/Q loads in flight, counted vmcnt) + V stored in 16-key blocked layout by phase 2 instead of Vt rows
# speedup vs baseline: 1.0464x; 1.0036x over previous
.LBB0_203:
	s_or_b64 exec, exec, s[16:17]
	s_load_dword s6, s[0:1], 0xd8
	v_and_b32_e32 v1, 63, v0
	v_lshlrev_b32_e32 v2, 1, v1
	v_lshlrev_b32_e32 v3, 5, v1
	v_readfirstlane_b32 s7, v130
	s_lshl_b32 s8, s2, 3
	s_nop 0
	s_add_u32 s8, s8, s7
	s_waitcnt lgkmcnt(0)
	s_lshl_b32 s6, s6, 3
	s_cmp_lt_u32 s8, 0x800
	s_cbranch_scc0 .Lvb_done
.Lvb_loop:
	s_lshr_b32 s9, s8, 10
	s_bfe_u32 s10, s8, 0x80002
	s_and_b32 s11, s8, 3
	s_lshl_b32 s12, s9, 8
	s_add_u32 s12, s12, s10
	s_mul_i32 s12, s12, 0x28000
	s_lshl_b32 s13, s11, 7
	s_add_u32 s12, s12, s13
	s_add_u32 s12, s12, 0x2600
	s_add_u32 s16, s70, s12
	s_addc_u32 s17, s71, 0
	s_add_u32 s16, s16, 0x7900000
	s_addc_u32 s17, s17, 0
	global_load_ushort v10, v2, s[16:17]
	s_add_u32 s16, s16, 0x2800
	s_addc_u32 s17, s17, 0
	global_load_ushort v11, v2, s[16:17]
	s_add_u32 s16, s16, 0x2800
	s_addc_u32 s17, s17, 0
	global_load_ushort v12, v2, s[16:17]
	s_add_u32 s16, s16, 0x2800
	s_addc_u32 s17, s17, 0
	global_load_ushort v13, v2, s[16:17]
	s_add_u32 s16, s16, 0x2800
	s_addc_u32 s17, s17, 0
	global_load_ushort v14, v2, s[16:17]
	s_add_u32 s16, s16, 0x2800
	s_addc_u32 s17, s17, 0
	global_load_ushort v15, v2, s[16:17]
	s_add_u32 s16, s16, 0x2800
	s_addc_u32 s17, s17, 0
	global_load_ushort v16, v2, s[16:17]
	s_add_u32 s16, s16, 0x2800
	s_addc_u32 s17, s17, 0
	global_load_ushort v17, v2, s[16:17]
	s_add_u32 s16, s16, 0x2800
	s_addc_u32 s17, s17, 0
	global_load_ushort v18, v2, s[16:17]
	s_add_u32 s16, s16, 0x2800
	s_addc_u32 s17, s17, 0
	global_load_ushort v19, v2, s[16:17]
	s_add_u32 s16, s16, 0x2800
	s_addc_u32 s17, s17, 0
	global_load_ushort v20, v2, s[16:17]
	s_add_u32 s16, s16, 0x2800
	s_addc_u32 s17, s17, 0
	global_load_ushort v21, v2, s[16:17]
	s_add_u32 s16, s16, 0x2800
	s_addc_u32 s17, s17, 0
	global_load_ushort v22, v2, s[16:17]
	s_add_u32 s16, s16, 0x2800
	s_addc_u32 s17, s17, 0
	global_load_ushort v23, v2, s[16:17]
	s_add_u32 s16, s16, 0x2800
	s_addc_u32 s17, s17, 0
	global_load_ushort v24, v2, s[16:17]
	s_add_u32 s16, s16, 0x2800
	s_addc_u32 s17, s17, 0
	global_load_ushort v25, v2, s[16:17]
	s_lshl_b32 s12, s9, 2
	s_add_u32 s12, s12, s11
	s_lshl_b32 s12, s12, 8
	s_add_u32 s12, s12, s10
	s_lshl_b32 s12, s12, 11
	s_add_u32 s18, s70, s12
	s_addc_u32 s19, s71, 0
	s_add_u32 s18, s18, 0x13500000
	s_addc_u32 s19, s19, 0
	s_waitcnt vmcnt(0)
	v_lshl_or_b32 v30, v11, 16, v10
	v_lshl_or_b32 v31, v13, 16, v12
	v_lshl_or_b32 v32, v15, 16, v14
	v_lshl_or_b32 v33, v17, 16, v16
	v_lshl_or_b32 v34, v19, 16, v18
	v_lshl_or_b32 v35, v21, 16, v20
	v_lshl_or_b32 v36, v23, 16, v22
	v_lshl_or_b32 v37, v25, 16, v24
	global_store_dwordx4 v3, v[30:33], s[18:19]
	global_store_dwordx4 v3, v[34:37], s[18:19] offset:16
	s_add_u32 s8, s8, s6
	s_cmp_lt_u32 s8, 0x800
	s_cbranch_scc1 .Lvb_loop
.Lvb_done:
.LBB0_206:
	s_cmp_gt_i32 s35, 3
	s_cselect_b64 s[6:7], -1, 0
	s_and_b64 s[6:7], s[14:15], s[6:7]
	s_andn2_b64 vcc, exec, s[6:7]
	s_cbranch_vccnz .LBB0_260
	s_waitcnt vmcnt(0)
	s_waitcnt lgkmcnt(0)
	s_barrier
	s_and_saveexec_b64 s[6:7], s[4:5]
	s_cbranch_execz .LBB0_259
	s_add_i32 s3, 0, 0x20000
	v_mov_b32_e32 v1, s3
	s_waitcnt vmcnt(0) expcnt(0) lgkmcnt(0)
	ds_read_b32 v3, v1
	s_add_i32 s3, 0, 0x20004
	v_mov_b32_e32 v1, s3
	ds_read_b32 v1, v1
	s_waitcnt lgkmcnt(1)
	v_cmp_ne_u32_e32 vcc, 0, v3
	s_cbranch_vccnz .LBB0_223
	s_load_dwordx2 s[12:13], s[0:1], 0xd8
	s_load_dword s3, s[0:1], 0xe0
	s_add_u32 s8, s70, 0x15c88300
	s_addc_u32 s9, s71, 0
	s_add_u32 s10, s70, 0x15c88500
	s_waitcnt lgkmcnt(0)
	s_mul_i32 s11, s13, s12
	s_mul_i32 s3, s11, s3
	s_addc_u32 s11, s71, 0
	s_add_u32 s12, s70, 0x15c88600
	s_addc_u32 s13, s71, 0
	s_add_u32 s14, s70, 0x15c88700
	s_addc_u32 s15, s71, 0
	s_add_u32 s16, s70, 0x15c88800
	s_addc_u32 s17, s71, 0
	s_add_u32 s18, s70, 0x15c88900
	s_addc_u32 s19, s71, 0
	s_add_u32 s20, s70, 0x15c88a00
	s_addc_u32 s21, s71, 0
	s_add_u32 s22, s70, 0x15c88b00
	s_addc_u32 s23, s71, 0
	s_add_u32 s24, s70, 0x15c88c00
	s_addc_u32 s25, s71, 0
	s_add_u32 s26, s70, 0x15c88d00
	s_addc_u32 s27, s71, 0
	s_add_u32 s28, s70, 0x15c88e00
	s_addc_u32 s29, s71, 0
	s_add_u32 s30, s70, 0x15c88f00
	s_addc_u32 s31, s71, 0
	s_add_u32 s42, s70, 0x15c89000
	s_addc_u32 s43, s71, 0
	s_add_u32 s46, s70, 0x15c89100
	s_addc_u32 s47, s71, 0
	s_add_u32 s50, s70, 0x15c89200
	s_addc_u32 s51, s71, 0
	s_add_u32 s52, s70, 0x15c89300
	s_addc_u32 s53, s71, 0
	s_add_u32 s64, s70, 0x15c89400
	s_addc_u32 s65, s71, 0
	s_mov_b32 s72, 1
	v_mov_b32_e32 v17, 0
	s_branch .LBB0_211

.LBB0_380:
	s_cmp_lt_i32 s34, 6
	s_cselect_b64 s[8:9], -1, 0
	v_writelane_b32 v255, s8, 2
	s_and_b64 s[6:7], s[8:9], s[6:7]
	s_andn2_b64 vcc, exec, s[6:7]
	v_writelane_b32 v255, s9, 3
	s_cbranch_vccnz .LBB0_571
	s_cmp_gt_i32 s2, 31
	s_cbranch_scc0 .LBB0_403
	v_and_b32_e32 v1, 63, v0
	v_and_b32_e32 v14, 15, v1
	v_lshrrev_b32_e32 v5, 4, v1
	v_xor_b32_e32 v11, 16, v1
	v_lshlrev_b32_e32 v11, 2, v11
	v_xor_b32_e32 v12, 32, v1
	v_lshlrev_b32_e32 v12, 2, v12
	v_lshlrev_b32_e32 v13, 11, v14
	v_lshl_add_u32 v13, v5, 4, v13
	v_lshlrev_b32_e32 v15, 4, v5
	v_lshlrev_b32_e32 v6, 2, v5
	v_sub_u32_e32 v7, v14, v6
	v_add_u32_e32 v7, 0x90, v7
	v_cvt_f32_i32_e32 v16, v7
	v_lshlrev_b32_e32 v17, 13, v5
	v_lshl_add_u32 v17, v14, 1, v17
	v_add_u32_e32 v18, 0x1000, v17
	v_lshlrev_b32_e32 v19, 5, v14
	v_lshl_add_u32 v19, v5, 3, v19
	v_mov_b32_e32 v20, v6
	v_mov_b32_e32 v133, 0xf149f2ca
	v_add_u32_e32 v7, 0, v6
	v_cmp_lt_u32_e64 s[74:75], v14, v7
	v_cmp_ge_u32_e64 s[82:83], v14, v7
	v_add_u32_e32 v7, 1, v6
	v_cmp_lt_u32_e64 s[76:77], v14, v7
	v_cmp_ge_u32_e64 s[84:85], v14, v7
	v_add_u32_e32 v7, 2, v6
	v_cmp_lt_u32_e64 s[78:79], v14, v7
	v_cmp_ge_u32_e64 s[86:87], v14, v7
	v_add_u32_e32 v7, 3, v6
	v_cmp_lt_u32_e64 s[80:81], v14, v7
	v_cmp_ge_u32_e64 s[88:89], v14, v7
	s_load_dword s6, s[0:1], 0xd8
	v_readfirstlane_b32 s7, v130
	s_sub_u32 s3, s2, 32
	s_lshl_b32 s3, s3, 3
	s_nop 0
	s_add_u32 s3, s3, s7
	s_waitcnt lgkmcnt(0)
	s_sub_u32 s6, s6, 32
	s_lshl_b32 s6, s6, 3
.Lat_loop:
	s_and_b32 s27, s3, 15
	s_bfe_u32 s28, s3, 0x80004
	s_lshr_b32 s29, s3, 12
	s_lshr_b32 s30, s27, 2
	s_lshl_b32 s31, s28, 4
	s_lshl_b32 s93, s27, 2
	s_load_dword s26, s[44:45], s93
	s_lshl_b32 s90, s29, 12
	s_add_u32 s90, s90, s31
	s_lshl_b32 s91, s90, 11
	s_lshl_b32 s92, s27, 7
	s_add_u32 s91, s91, s92
	s_add_u32 s8, s68, s91
	s_addc_u32 s9, s69, 0
	s_add_u32 s8, s8, 0x3000000
	s_addc_u32 s9, s9, 0
	s_add_u32 s20, s70, s91
	s_addc_u32 s21, s71, 0
	s_add_u32 s20, s20, 0x13900000
	s_addc_u32 s21, s21, 0
	s_lshl_b32 s94, s29, 21
	s_lshl_b32 s95, s30, 7
	s_add_u32 s94, s94, s95
	s_add_u32 s10, s70, s94
	s_addc_u32 s11, s71, 0
	s_add_u32 s10, s10, 0x13100000
	s_addc_u32 s11, s11, 0
	s_lshl_b32 s94, s29, 2
	s_add_u32 s94, s94, s30
	s_lshl_b32 s94, s94, 19
	s_add_u32 s12, s70, s94
	s_addc_u32 s13, s71, 0
	s_add_u32 s12, s12, 0x13500000
	s_addc_u32 s13, s13, 0
	s_add_i32 s22, s31, 0xffffff70
	s_sub_i32 s23, 9, s28
	s_max_i32 s23, s23, 0
	s_add_u32 s24, s27, 1
	v_cvt_f32_u32_e32 v21, s24
	v_mul_f32_e32 v21, -0.5, v21
	v_exp_f32_e32 v132, v21
	global_load_dwordx4 v[30:33], v13, s[8:9]
	global_load_dwordx4 v[34:37], v13, s[8:9] offset:64
	v_add_u32_e32 v21, s22, v14
	v_max_i32_e32 v22, 0, v21
	v_lshl_add_u32 v22, v22, 9, v15
	global_load_dwordx4 v[40:43], v22, s[10:11]
	global_load_dwordx4 v[44:47], v22, s[10:11] offset:64
	v_add_u32_e32 v22, 16, v21
	v_max_i32_e32 v22, 0, v22
	v_lshl_add_u32 v22, v22, 9, v15
	global_load_dwordx4 v[48:51], v22, s[10:11]
	global_load_dwordx4 v[52:55], v22, s[10:11] offset:64
	v_add_u32_e32 v22, 32, v21
	v_max_i32_e32 v22, 0, v22
	v_lshl_add_u32 v22, v22, 9, v15
	global_load_dwordx4 v[56:59], v22, s[10:11]
	global_load_dwordx4 v[60:63], v22, s[10:11] offset:64
	v_add_u32_e32 v22, 48, v21
	v_max_i32_e32 v22, 0, v22
	v_lshl_add_u32 v22, v22, 9, v15
	global_load_dwordx4 v[64:67], v22, s[10:11]
	global_load_dwordx4 v[68:71], v22, s[10:11] offset:64
	v_add_u32_e32 v22, 64, v21
	v_max_i32_e32 v22, 0, v22
	v_lshl_add_u32 v22, v22, 9, v15
	global_load_dwordx4 v[72:75], v22, s[10:11]
	global_load_dwordx4 v[76:79], v22, s[10:11] offset:64
	v_add_u32_e32 v22, 80, v21
	v_max_i32_e32 v22, 0, v22
	v_lshl_add_u32 v22, v22, 9, v15
	global_load_dwordx4 v[80:83], v22, s[10:11]
	global_load_dwordx4 v[84:87], v22, s[10:11] offset:64
	v_add_u32_e32 v22, 96, v21
	v_max_i32_e32 v22, 0, v22
	v_lshl_add_u32 v22, v22, 9, v15
	global_load_dwordx4 v[88:91], v22, s[10:11]
	global_load_dwordx4 v[92:95], v22, s[10:11] offset:64
	v_add_u32_e32 v22, 112, v21
	v_max_i32_e32 v22, 0, v22
	v_lshl_add_u32 v22, v22, 9, v15
	global_load_dwordx4 v[96:99], v22, s[10:11]
	global_load_dwordx4 v[100:103], v22, s[10:11] offset:64
	v_add_u32_e32 v22, 128, v21
	v_max_i32_e32 v22, 0, v22
	v_lshl_add_u32 v22, v22, 9, v15
	global_load_dwordx4 v[104:107], v22, s[10:11]
	global_load_dwordx4 v[108:111], v22, s[10:11] offset:64
	v_add_u32_e32 v22, 144, v21
	v_max_i32_e32 v22, 0, v22
	v_lshl_add_u32 v22, v22, 9, v15
	global_load_dwordx4 v[112:115], v22, s[10:11]
	global_load_dwordx4 v[116:119], v22, s[10:11] offset:64
	s_add_i32 s14, s28, -9
	s_max_i32 s14, s14, 0
	s_lshl_b32 s14, s14, 11
	s_add_u32 s16, s12, s14
	s_addc_u32 s17, s13, 0
	global_load_dwordx2 v[160:161], v19, s[16:17]
	global_load_dwordx2 v[164:165], v19, s[16:17] offset:512
	global_load_dwordx2 v[168:169], v19, s[16:17] offset:1024
	global_load_dwordx2 v[172:173], v19, s[16:17] offset:1536
	s_add_i32 s14, s28, -8
	s_max_i32 s14, s14, 0
	s_lshl_b32 s14, s14, 11
	s_add_u32 s16, s12, s14
	s_addc_u32 s17, s13, 0
	global_load_dwordx2 v[162:163], v19, s[16:17]
	global_load_dwordx2 v[166:167], v19, s[16:17] offset:512
	global_load_dwordx2 v[170:171], v19, s[16:17] offset:1024
	global_load_dwordx2 v[174:175], v19, s[16:17] offset:1536
	s_add_i32 s14, s28, -7
	s_max_i32 s14, s14, 0
	s_lshl_b32 s14, s14, 11
	s_add_u32 s16, s12, s14
	s_addc_u32 s17, s13, 0
	global_load_dwordx2 v[176:177], v19, s[16:17]
	global_load_dwordx2 v[180:181], v19, s[16:17] offset:512
	global_load_dwordx2 v[184:185], v19, s[16:17] offset:1024
	global_load_dwordx2 v[188:189], v19, s[16:17] offset:1536
	s_add_i32 s14, s28, -6
	s_max_i32 s14, s14, 0
	s_lshl_b32 s14, s14, 11
	s_add_u32 s16, s12, s14
	s_addc_u32 s17, s13, 0
	global_load_dwordx2 v[178:179], v19, s[16:17]
	global_load_dwordx2 v[182:183], v19, s[16:17] offset:512
	global_load_dwordx2 v[186:187], v19, s[16:17] offset:1024
	global_load_dwordx2 v[190:191], v19, s[16:17] offset:1536
	s_add_i32 s14, s28, -5
	s_max_i32 s14, s14, 0
	s_lshl_b32 s14, s14, 11
	s_add_u32 s16, s12, s14
	s_addc_u32 s17, s13, 0
	global_load_dwordx2 v[192:193], v19, s[16:17]
	global_load_dwordx2 v[196:197], v19, s[16:17] offset:512
	global_load_dwordx2 v[200:201], v19, s[16:17] offset:1024
	global_load_dwordx2 v[204:205], v19, s[16:17] offset:1536
	s_add_i32 s14, s28, -4
	s_max_i32 s14, s14, 0
	s_lshl_b32 s14, s14, 11
	s_add_u32 s16, s12, s14
	s_addc_u32 s17, s13, 0
	global_load_dwordx2 v[194:195], v19, s[16:17]
	global_load_dwordx2 v[198:199], v19, s[16:17] offset:512
	global_load_dwordx2 v[202:203], v19, s[16:17] offset:1024
	global_load_dwordx2 v[206:207], v19, s[16:17] offset:1536
	s_add_i32 s14, s28, -3
	s_max_i32 s14, s14, 0
	s_lshl_b32 s14, s14, 11
	s_add_u32 s16, s12, s14
	s_addc_u32 s17, s13, 0
	global_load_dwordx2 v[208:209], v19, s[16:17]
	global_load_dwordx2 v[212:213], v19, s[16:17] offset:512
	global_load_dwordx2 v[216:217], v19, s[16:17] offset:1024
	global_load_dwordx2 v[220:221], v19, s[16:17] offset:1536
	s_add_i32 s14, s28, -2
	s_max_i32 s14, s14, 0
	s_lshl_b32 s14, s14, 11
	s_add_u32 s16, s12, s14
	s_addc_u32 s17, s13, 0
	global_load_dwordx2 v[210:211], v19, s[16:17]
	global_load_dwordx2 v[214:215], v19, s[16:17] offset:512
	global_load_dwordx2 v[218:219], v19, s[16:17] offset:1024
	global_load_dwordx2 v[222:223], v19, s[16:17] offset:1536
	s_add_i32 s14, s28, -1
	s_max_i32 s14, s14, 0
	s_lshl_b32 s14, s14, 11
	s_add_u32 s16, s12, s14
	s_addc_u32 s17, s13, 0
	global_load_dwordx2 v[224:225], v19, s[16:17]
	global_load_dwordx2 v[228:229], v19, s[16:17] offset:512
	global_load_dwordx2 v[232:233], v19, s[16:17] offset:1024
	global_load_dwordx2 v[236:237], v19, s[16:17] offset:1536
	s_add_i32 s14, s28, 0
	s_max_i32 s14, s14, 0
	s_lshl_b32 s14, s14, 11
	s_add_u32 s16, s12, s14
	s_addc_u32 s17, s13, 0
	global_load_dwordx2 v[226:227], v19, s[16:17]
	global_load_dwordx2 v[230:231], v19, s[16:17] offset:512
	global_load_dwordx2 v[234:235], v19, s[16:17] offset:1024
	global_load_dwordx2 v[238:239], v19, s[16:17] offset:1536
	v_sub_f32_e32 v132, 0, v132
	s_waitcnt lgkmcnt(0)
	v_mov_b32_e32 v128, s26
	s_waitcnt vmcnt(58)
	v_mfma_f32_16x16x32_bf16 v[40:43], v[40:43], v[30:33], 0
	v_mfma_f32_16x16x32_bf16 v[40:43], v[44:47], v[34:37], v[40:43]
	s_waitcnt vmcnt(56)
	v_mfma_f32_16x16x32_bf16 v[48:51], v[48:51], v[30:33], 0
	v_mfma_f32_16x16x32_bf16 v[48:51], v[52:55], v[34:37], v[48:51]
	s_waitcnt vmcnt(54)
	v_mfma_f32_16x16x32_bf16 v[56:59], v[56:59], v[30:33], 0
	v_mfma_f32_16x16x32_bf16 v[56:59], v[60:63], v[34:37], v[56:59]
	s_waitcnt vmcnt(52)
	v_mfma_f32_16x16x32_bf16 v[64:67], v[64:67], v[30:33], 0
	v_mfma_f32_16x16x32_bf16 v[64:67], v[68:71], v[34:37], v[64:67]
	s_waitcnt vmcnt(50)
	v_mfma_f32_16x16x32_bf16 v[72:75], v[72:75], v[30:33], 0
	v_mfma_f32_16x16x32_bf16 v[72:75], v[76:79], v[34:37], v[72:75]
	s_waitcnt vmcnt(48)
	v_mfma_f32_16x16x32_bf16 v[80:83], v[80:83], v[30:33], 0
	v_mfma_f32_16x16x32_bf16 v[80:83], v[84:87], v[34:37], v[80:83]
	s_waitcnt vmcnt(46)
	v_mfma_f32_16x16x32_bf16 v[88:91], v[88:91], v[30:33], 0
	v_mfma_f32_16x16x32_bf16 v[88:91], v[92:95], v[34:37], v[88:91]
	s_waitcnt vmcnt(44)
	v_mfma_f32_16x16x32_bf16 v[96:99], v[96:99], v[30:33], 0
	v_mfma_f32_16x16x32_bf16 v[96:99], v[100:103], v[34:37], v[96:99]
	s_waitcnt vmcnt(42)
	v_mfma_f32_16x16x32_bf16 v[104:107], v[104:107], v[30:33], 0
	v_mfma_f32_16x16x32_bf16 v[104:107], v[108:111], v[34:37], v[104:107]
	s_waitcnt vmcnt(40)
	v_mfma_f32_16x16x32_bf16 v[112:115], v[112:115], v[30:33], 0
	v_mfma_f32_16x16x32_bf16 v[112:115], v[116:119], v[34:37], v[112:115]
	v_mov_b32_e32 v40, v133
	v_mov_b32_e32 v41, v133
	v_mov_b32_e32 v42, v133
	v_mov_b32_e32 v43, v133
	v_subrev_f32_e32 v21, 0x41800000, v16
	v_subrev_f32_e32 v22, 0x41880000, v16
	v_subrev_f32_e32 v23, 0x41900000, v16
	v_subrev_f32_e32 v24, 0x41980000, v16
	v_fma_f32 v48, v132, v21, v48
	v_fma_f32 v49, v132, v22, v49
	v_fma_f32 v50, v132, v23, v50
	v_fma_f32 v51, v132, v24, v51
	v_cndmask_b32_e64 v48, v133, v48, s[74:75]
	v_cndmask_b32_e64 v49, v133, v49, s[76:77]
	v_cndmask_b32_e64 v50, v133, v50, s[78:79]
	v_cndmask_b32_e64 v51, v133, v51, s[80:81]
	s_cmp_lt_u32 s23, 2
	s_cbranch_scc1 .Lat_ok_1
	v_mov_b32_e32 v48, v133
	v_mov_b32_e32 v49, v133
	v_mov_b32_e32 v50, v133
	v_mov_b32_e32 v51, v133
.Lat_ok_1:
	v_max3_f32 v128, v128, v48, v49
	v_max3_f32 v128, v128, v50, v51
	v_subrev_f32_e32 v21, 0x42000000, v16
	v_subrev_f32_e32 v22, 0x42040000, v16
	v_subrev_f32_e32 v23, 0x42080000, v16
	v_subrev_f32_e32 v24, 0x420c0000, v16
	v_fma_f32 v56, v132, v21, v56
	v_fma_f32 v57, v132, v22, v57
	v_fma_f32 v58, v132, v23, v58
	v_fma_f32 v59, v132, v24, v59
	s_cmp_lt_u32 s23, 3
	s_cbranch_scc1 .Lat_ok_2
	v_mov_b32_e32 v56, v133
	v_mov_b32_e32 v57, v133
	v_mov_b32_e32 v58, v133
	v_mov_b32_e32 v59, v133
.Lat_ok_2:
	v_max3_f32 v128, v128, v56, v57
	v_max3_f32 v128, v128, v58, v59
	v_subrev_f32_e32 v21, 0x42400000, v16
	v_subrev_f32_e32 v22, 0x42440000, v16
	v_subrev_f32_e32 v23, 0x42480000, v16
	v_subrev_f32_e32 v24, 0x424c0000, v16
	v_fma_f32 v64, v132, v21, v64
	v_fma_f32 v65, v132, v22, v65
	v_fma_f32 v66, v132, v23, v66
	v_fma_f32 v67, v132, v24, v67
	s_cmp_lt_u32 s23, 4
	s_cbranch_scc1 .Lat_ok_3
	v_mov_b32_e32 v64, v133
	v_mov_b32_e32 v65, v133
	v_mov_b32_e32 v66, v133
	v_mov_b32_e32 v67, v133
.Lat_ok_3:
	v_max3_f32 v128, v128, v64, v65
	v_max3_f32 v128, v128, v66, v67
	v_subrev_f32_e32 v21, 0x42800000, v16
	v_subrev_f32_e32 v22, 0x42820000, v16
	v_subrev_f32_e32 v23, 0x42840000, v16
	v_subrev_f32_e32 v24, 0x42860000, v16
	v_fma_f32 v72, v132, v21, v72
	v_fma_f32 v73, v132, v22, v73
	v_fma_f32 v74, v132, v23, v74
	v_fma_f32 v75, v132, v24, v75
	s_cmp_lt_u32 s23, 5
	s_cbranch_scc1 .Lat_ok_4
	v_mov_b32_e32 v72, v133
	v_mov_b32_e32 v73, v133
	v_mov_b32_e32 v74, v133
	v_mov_b32_e32 v75, v133
.Lat_ok_4:
	v_max3_f32 v128, v128, v72, v73
	v_max3_f32 v128, v128, v74, v75
	v_subrev_f32_e32 v21, 0x42a00000, v16
	v_subrev_f32_e32 v22, 0x42a20000, v16
	v_subrev_f32_e32 v23, 0x42a40000, v16
	v_subrev_f32_e32 v24, 0x42a60000, v16
	v_fma_f32 v80, v132, v21, v80
	v_fma_f32 v81, v132, v22, v81
	v_fma_f32 v82, v132, v23, v82
	v_fma_f32 v83, v132, v24, v83
	s_cmp_lt_u32 s23, 6
	s_cbranch_scc1 .Lat_ok_5
	v_mov_b32_e32 v80, v133
	v_mov_b32_e32 v81, v133
	v_mov_b32_e32 v82, v133
	v_mov_b32_e32 v83, v133
.Lat_ok_5:
	v_max3_f32 v128, v128, v80, v81
	v_max3_f32 v128, v128, v82, v83
	v_subrev_f32_e32 v21, 0x42c00000, v16
	v_subrev_f32_e32 v22, 0x42c20000, v16
	v_subrev_f32_e32 v23, 0x42c40000, v16
	v_subrev_f32_e32 v24, 0x42c60000, v16
	v_fma_f32 v88, v132, v21, v88
	v_fma_f32 v89, v132, v22, v89
	v_fma_f32 v90, v132, v23, v90
	v_fma_f32 v91, v132, v24, v91
	s_cmp_lt_u32 s23, 7
	s_cbranch_scc1 .Lat_ok_6
	v_mov_b32_e32 v88, v133
	v_mov_b32_e32 v89, v133
	v_mov_b32_e32 v90, v133
	v_mov_b32_e32 v91, v133
.Lat_ok_6:
	v_max3_f32 v128, v128, v88, v89
	v_max3_f32 v128, v128, v90, v91
	v_subrev_f32_e32 v21, 0x42e00000, v16
	v_subrev_f32_e32 v22, 0x42e20000, v16
	v_subrev_f32_e32 v23, 0x42e40000, v16
	v_subrev_f32_e32 v24, 0x42e60000, v16
	v_fma_f32 v96, v132, v21, v96
	v_fma_f32 v97, v132, v22, v97
	v_fma_f32 v98, v132, v23, v98
	v_fma_f32 v99, v132, v24, v99
	s_cmp_lt_u32 s23, 8
	s_cbranch_scc1 .Lat_ok_7
	v_mov_b32_e32 v96, v133
	v_mov_b32_e32 v97, v133
	v_mov_b32_e32 v98, v133
	v_mov_b32_e32 v99, v133
.Lat_ok_7:
	v_max3_f32 v128, v128, v96, v97
	v_max3_f32 v128, v128, v98, v99
	v_subrev_f32_e32 v21, 0x43000000, v16
	v_subrev_f32_e32 v22, 0x43010000, v16
	v_subrev_f32_e32 v23, 0x43020000, v16
	v_subrev_f32_e32 v24, 0x43030000, v16
	v_fma_f32 v104, v132, v21, v104
	v_fma_f32 v105, v132, v22, v105
	v_fma_f32 v106, v132, v23, v106
	v_fma_f32 v107, v132, v24, v107
	s_cmp_lt_u32 s23, 9
	s_cbranch_scc1 .Lat_ok_8
	v_mov_b32_e32 v104, v133
	v_mov_b32_e32 v105, v133
	v_mov_b32_e32 v106, v133
	v_mov_b32_e32 v107, v133
.Lat_ok_8:
	v_max3_f32 v128, v128, v104, v105
	v_max3_f32 v128, v128, v106, v107
	v_subrev_f32_e32 v21, 0x43100000, v16
	v_subrev_f32_e32 v22, 0x43110000, v16
	v_subrev_f32_e32 v23, 0x43120000, v16
	v_subrev_f32_e32 v24, 0x43130000, v16
	v_fma_f32 v112, v132, v21, v112
	v_fma_f32 v113, v132, v22, v113
	v_fma_f32 v114, v132, v23, v114
	v_fma_f32 v115, v132, v24, v115
	v_cndmask_b32_e64 v112, v133, v112, s[82:83]
	v_cndmask_b32_e64 v113, v133, v113, s[84:85]
	v_cndmask_b32_e64 v114, v133, v114, s[86:87]
	v_cndmask_b32_e64 v115, v133, v115, s[88:89]
	v_max3_f32 v128, v128, v112, v113
	v_max3_f32 v128, v128, v114, v115
	v_max_f32_e32 v128, v128, v128
	ds_bpermute_b32 v21, v11, v128
	s_waitcnt lgkmcnt(0)
	v_max_f32_e32 v21, v21, v21
	v_max_f32_e32 v128, v128, v21
	ds_bpermute_b32 v21, v12, v128
	s_waitcnt lgkmcnt(0)
	v_max_f32_e32 v21, v21, v21
	v_max_f32_e32 v128, v128, v21
	v_mov_b32_e32 v129, 0
	v_sub_f32_e32 v40, v40, v128
	v_sub_f32_e32 v41, v41, v128
	v_sub_f32_e32 v42, v42, v128
	v_sub_f32_e32 v43, v43, v128
	v_sub_f32_e32 v48, v48, v128
	v_sub_f32_e32 v49, v49, v128
	v_sub_f32_e32 v50, v50, v128
	v_sub_f32_e32 v51, v51, v128
	v_sub_f32_e32 v56, v56, v128
	v_sub_f32_e32 v57, v57, v128
	v_sub_f32_e32 v58, v58, v128
	v_sub_f32_e32 v59, v59, v128
	v_sub_f32_e32 v64, v64, v128
	v_sub_f32_e32 v65, v65, v128
	v_sub_f32_e32 v66, v66, v128
	v_sub_f32_e32 v67, v67, v128
	v_sub_f32_e32 v72, v72, v128
	v_sub_f32_e32 v73, v73, v128
	v_sub_f32_e32 v74, v74, v128
	v_sub_f32_e32 v75, v75, v128
	v_sub_f32_e32 v80, v80, v128
	v_sub_f32_e32 v81, v81, v128
	v_sub_f32_e32 v82, v82, v128
	v_sub_f32_e32 v83, v83, v128
	v_sub_f32_e32 v88, v88, v128
	v_sub_f32_e32 v89, v89, v128
	v_sub_f32_e32 v90, v90, v128
	v_sub_f32_e32 v91, v91, v128
	v_sub_f32_e32 v96, v96, v128
	v_sub_f32_e32 v97, v97, v128
	v_sub_f32_e32 v98, v98, v128
	v_sub_f32_e32 v99, v99, v128
	v_sub_f32_e32 v104, v104, v128
	v_sub_f32_e32 v105, v105, v128
	v_sub_f32_e32 v106, v106, v128
	v_sub_f32_e32 v107, v107, v128
	v_sub_f32_e32 v112, v112, v128
	v_sub_f32_e32 v113, v113, v128
	v_sub_f32_e32 v114, v114, v128
	v_sub_f32_e32 v115, v115, v128
	v_mul_f32_e32 v40, 0x3fb8aa3b, v40
	v_mul_f32_e32 v41, 0x3fb8aa3b, v41
	v_mul_f32_e32 v42, 0x3fb8aa3b, v42
	v_mul_f32_e32 v43, 0x3fb8aa3b, v43
	v_mul_f32_e32 v48, 0x3fb8aa3b, v48
	v_mul_f32_e32 v49, 0x3fb8aa3b, v49
	v_mul_f32_e32 v50, 0x3fb8aa3b, v50
	v_mul_f32_e32 v51, 0x3fb8aa3b, v51
	v_mul_f32_e32 v56, 0x3fb8aa3b, v56
	v_mul_f32_e32 v57, 0x3fb8aa3b, v57
	v_mul_f32_e32 v58, 0x3fb8aa3b, v58
	v_mul_f32_e32 v59, 0x3fb8aa3b, v59
	v_mul_f32_e32 v64, 0x3fb8aa3b, v64
	v_mul_f32_e32 v65, 0x3fb8aa3b, v65
	v_mul_f32_e32 v66, 0x3fb8aa3b, v66
	v_mul_f32_e32 v67, 0x3fb8aa3b, v67
	v_mul_f32_e32 v72, 0x3fb8aa3b, v72
	v_mul_f32_e32 v73, 0x3fb8aa3b, v73
	v_mul_f32_e32 v74, 0x3fb8aa3b, v74
	v_mul_f32_e32 v75, 0x3fb8aa3b, v75
	v_mul_f32_e32 v80, 0x3fb8aa3b, v80
	v_mul_f32_e32 v81, 0x3fb8aa3b, v81
	v_mul_f32_e32 v82, 0x3fb8aa3b, v82
	v_mul_f32_e32 v83, 0x3fb8aa3b, v83
	v_mul_f32_e32 v88, 0x3fb8aa3b, v88
	v_mul_f32_e32 v89, 0x3fb8aa3b, v89
	v_mul_f32_e32 v90, 0x3fb8aa3b, v90
	v_mul_f32_e32 v91, 0x3fb8aa3b, v91
	v_mul_f32_e32 v96, 0x3fb8aa3b, v96
	v_mul_f32_e32 v97, 0x3fb8aa3b, v97
	v_mul_f32_e32 v98, 0x3fb8aa3b, v98
	v_mul_f32_e32 v99, 0x3fb8aa3b, v99
	v_mul_f32_e32 v104, 0x3fb8aa3b, v104
	v_mul_f32_e32 v105, 0x3fb8aa3b, v105
	v_mul_f32_e32 v106, 0x3fb8aa3b, v106
	v_mul_f32_e32 v107, 0x3fb8aa3b, v107
	v_mul_f32_e32 v112, 0x3fb8aa3b, v112
	v_mul_f32_e32 v113, 0x3fb8aa3b, v113
	v_mul_f32_e32 v114, 0x3fb8aa3b, v114
	v_mul_f32_e32 v115, 0x3fb8aa3b, v115
	v_exp_f32_e32 v40, v40
	v_exp_f32_e32 v41, v41
	v_exp_f32_e32 v42, v42
	v_exp_f32_e32 v43, v43
	v_exp_f32_e32 v48, v48
	v_exp_f32_e32 v49, v49
	v_exp_f32_e32 v50, v50
	v_exp_f32_e32 v51, v51
	v_exp_f32_e32 v56, v56
	v_exp_f32_e32 v57, v57
	v_exp_f32_e32 v58, v58
	v_exp_f32_e32 v59, v59
	v_exp_f32_e32 v64, v64
	v_exp_f32_e32 v65, v65
	v_exp_f32_e32 v66, v66
	v_exp_f32_e32 v67, v67
	v_exp_f32_e32 v72, v72
	v_exp_f32_e32 v73, v73
	v_exp_f32_e32 v74, v74
	v_exp_f32_e32 v75, v75
	v_exp_f32_e32 v80, v80
	v_exp_f32_e32 v81, v81
	v_exp_f32_e32 v82, v82
	v_exp_f32_e32 v83, v83
	v_exp_f32_e32 v88, v88
	v_exp_f32_e32 v89, v89
	v_exp_f32_e32 v90, v90
	v_exp_f32_e32 v91, v91
	v_exp_f32_e32 v96, v96
	v_exp_f32_e32 v97, v97
	v_exp_f32_e32 v98, v98
	v_exp_f32_e32 v99, v99
	v_exp_f32_e32 v104, v104
	v_exp_f32_e32 v105, v105
	v_exp_f32_e32 v106, v106
	v_exp_f32_e32 v107, v107
	v_exp_f32_e32 v112, v112
	v_exp_f32_e32 v113, v113
	v_exp_f32_e32 v114, v114
	v_exp_f32_e32 v115, v115
	s_nop 0
	v_add_f32_e32 v129, v40, v129
	v_add_f32_e32 v129, v41, v129
	v_add_f32_e32 v129, v42, v129
	v_add_f32_e32 v129, v43, v129
	v_add_f32_e32 v129, v48, v129
	v_add_f32_e32 v129, v49, v129
	v_add_f32_e32 v129, v50, v129
	v_add_f32_e32 v129, v51, v129
	v_add_f32_e32 v129, v56, v129
	v_add_f32_e32 v129, v57, v129
	v_add_f32_e32 v129, v58, v129
	v_add_f32_e32 v129, v59, v129
	v_add_f32_e32 v129, v64, v129
	v_add_f32_e32 v129, v65, v129
	v_add_f32_e32 v129, v66, v129
	v_add_f32_e32 v129, v67, v129
	v_add_f32_e32 v129, v72, v129
	v_add_f32_e32 v129, v73, v129
	v_add_f32_e32 v129, v74, v129
	v_add_f32_e32 v129, v75, v129
	v_add_f32_e32 v129, v80, v129
	v_add_f32_e32 v129, v81, v129
	v_add_f32_e32 v129, v82, v129
	v_add_f32_e32 v129, v83, v129
	v_add_f32_e32 v129, v88, v129
	v_add_f32_e32 v129, v89, v129
	v_add_f32_e32 v129, v90, v129
	v_add_f32_e32 v129, v91, v129
	v_add_f32_e32 v129, v96, v129
	v_add_f32_e32 v129, v97, v129
	v_add_f32_e32 v129, v98, v129
	v_add_f32_e32 v129, v99, v129
	v_add_f32_e32 v129, v104, v129
	v_add_f32_e32 v129, v105, v129
	v_add_f32_e32 v129, v106, v129
	v_add_f32_e32 v129, v107, v129
	v_add_f32_e32 v129, v112, v129
	v_add_f32_e32 v129, v113, v129
	v_add_f32_e32 v129, v114, v129
	v_add_f32_e32 v129, v115, v129
	ds_bpermute_b32 v21, v11, v129
	s_waitcnt lgkmcnt(0)
	v_add_f32_e32 v129, v129, v21
	ds_bpermute_b32 v21, v12, v129
	s_waitcnt lgkmcnt(0)
	v_add_f32_e32 v129, v129, v21
	v_sub_f32_e32 v21, s26, v128
	v_mul_f32_e32 v21, 0x3fb8aa3b, v21
	v_exp_f32_e32 v21, v21
	s_nop 0
	v_add_f32_e32 v129, v21, v129
	v_div_scale_f32 v134, s[30:31], v129, v129, 1.0
	v_rcp_f32_e32 v135, v134
	s_nop 0
	v_fma_f32 v136, -v134, v135, 1.0
	v_fmac_f32_e32 v135, v136, v135
	v_div_scale_f32 v136, vcc, 1.0, v129, 1.0
	v_mul_f32_e32 v137, v136, v135
	v_fma_f32 v138, -v134, v137, v136
	v_fmac_f32_e32 v137, v138, v135
	v_fma_f32 v134, -v134, v137, v136
	v_div_fmas_f32 v134, v134, v135, v137
	v_div_fixup_f32 v131, v134, v129, 1.0
	v_mul_f32_e32 v40, v40, v131
	v_mul_f32_e32 v41, v41, v131
	v_mul_f32_e32 v42, v42, v131
	v_mul_f32_e32 v43, v43, v131
	v_mul_f32_e32 v48, v48, v131
	v_mul_f32_e32 v49, v49, v131
	v_mul_f32_e32 v50, v50, v131
	v_mul_f32_e32 v51, v51, v131
	v_mul_f32_e32 v56, v56, v131
	v_mul_f32_e32 v57, v57, v131
	v_mul_f32_e32 v58, v58, v131
	v_mul_f32_e32 v59, v59, v131
	v_mul_f32_e32 v64, v64, v131
	v_mul_f32_e32 v65, v65, v131
	v_mul_f32_e32 v66, v66, v131
	v_mul_f32_e32 v67, v67, v131
	v_mul_f32_e32 v72, v72, v131
	v_mul_f32_e32 v73, v73, v131
	v_mul_f32_e32 v74, v74, v131
	v_mul_f32_e32 v75, v75, v131
	v_mul_f32_e32 v80, v80, v131
	v_mul_f32_e32 v81, v81, v131
	v_mul_f32_e32 v82, v82, v131
	v_mul_f32_e32 v83, v83, v131
	v_mul_f32_e32 v88, v88, v131
	v_mul_f32_e32 v89, v89, v131
	v_mul_f32_e32 v90, v90, v131
	v_mul_f32_e32 v91, v91, v131
	v_mul_f32_e32 v96, v96, v131
	v_mul_f32_e32 v97, v97, v131
	v_mul_f32_e32 v98, v98, v131
	v_mul_f32_e32 v99, v99, v131
	v_mul_f32_e32 v104, v104, v131
	v_mul_f32_e32 v105, v105, v131
	v_mul_f32_e32 v106, v106, v131
	v_mul_f32_e32 v107, v107, v131
	v_mul_f32_e32 v112, v112, v131
	v_mul_f32_e32 v113, v113, v131
	v_mul_f32_e32 v114, v114, v131
	v_mul_f32_e32 v115, v115, v131
	v_cvt_pk_bf16_f32 v124, v40, v41
	v_cvt_pk_bf16_f32 v125, v42, v43
	v_cvt_pk_bf16_f32 v126, v48, v49
	v_cvt_pk_bf16_f32 v127, v50, v51
	s_waitcnt vmcnt(35)
	s_nop 0
	v_mfma_f32_16x16x32_bf16 v[240:243], v[124:127], v[160:163], 0
	s_waitcnt vmcnt(34)
	v_mfma_f32_16x16x32_bf16 v[244:247], v[124:127], v[164:167], 0
	s_waitcnt vmcnt(33)
	v_mfma_f32_16x16x32_bf16 v[248:251], v[124:127], v[168:171], 0
	s_waitcnt vmcnt(32)
	v_mfma_f32_16x16x32_bf16 v[120:123], v[124:127], v[172:175], 0
	v_cvt_pk_bf16_f32 v124, v56, v57
	v_cvt_pk_bf16_f32 v125, v58, v59
	v_cvt_pk_bf16_f32 v126, v64, v65
	v_cvt_pk_bf16_f32 v127, v66, v67
	s_waitcnt vmcnt(27)
	s_nop 0
	v_mfma_f32_16x16x32_bf16 v[240:243], v[124:127], v[176:179], v[240:243]
	s_waitcnt vmcnt(26)
	v_mfma_f32_16x16x32_bf16 v[244:247], v[124:127], v[180:183], v[244:247]
	s_waitcnt vmcnt(25)
	v_mfma_f32_16x16x32_bf16 v[248:251], v[124:127], v[184:187], v[248:251]
	s_waitcnt vmcnt(24)
	v_mfma_f32_16x16x32_bf16 v[120:123], v[124:127], v[188:191], v[120:123]
	v_cvt_pk_bf16_f32 v124, v72, v73
	v_cvt_pk_bf16_f32 v125, v74, v75
	v_cvt_pk_bf16_f32 v126, v80, v81
	v_cvt_pk_bf16_f32 v127, v82, v83
	s_waitcnt vmcnt(19)
	s_nop 0
	v_mfma_f32_16x16x32_bf16 v[240:243], v[124:127], v[192:195], v[240:243]
	s_waitcnt vmcnt(18)
	v_mfma_f32_16x16x32_bf16 v[244:247], v[124:127], v[196:199], v[244:247]
	s_waitcnt vmcnt(17)
	v_mfma_f32_16x16x32_bf16 v[248:251], v[124:127], v[200:203], v[248:251]
	s_waitcnt vmcnt(16)
	v_mfma_f32_16x16x32_bf16 v[120:123], v[124:127], v[204:207], v[120:123]
	v_cvt_pk_bf16_f32 v124, v88, v89
	v_cvt_pk_bf16_f32 v125, v90, v91
	v_cvt_pk_bf16_f32 v126, v96, v97
	v_cvt_pk_bf16_f32 v127, v98, v99
	s_waitcnt vmcnt(11)
	s_nop 0
	v_mfma_f32_16x16x32_bf16 v[240:243], v[124:127], v[208:211], v[240:243]
	s_waitcnt vmcnt(10)
	v_mfma_f32_16x16x32_bf16 v[244:247], v[124:127], v[212:215], v[244:247]
	s_waitcnt vmcnt(9)
	v_mfma_f32_16x16x32_bf16 v[248:251], v[124:127], v[216:219], v[248:251]
	s_waitcnt vmcnt(8)
	v_mfma_f32_16x16x32_bf16 v[120:123], v[124:127], v[220:223], v[120:123]
	v_cvt_pk_bf16_f32 v124, v104, v105
	v_cvt_pk_bf16_f32 v125, v106, v107
	v_cvt_pk_bf16_f32 v126, v112, v113
	v_cvt_pk_bf16_f32 v127, v114, v115
	s_waitcnt vmcnt(3)
	s_nop 0
	v_mfma_f32_16x16x32_bf16 v[240:243], v[124:127], v[224:227], v[240:243]
	s_waitcnt vmcnt(2)
	v_mfma_f32_16x16x32_bf16 v[244:247], v[124:127], v[228:231], v[244:247]
	s_waitcnt vmcnt(1)
	v_mfma_f32_16x16x32_bf16 v[248:251], v[124:127], v[232:235], v[248:251]
	s_waitcnt vmcnt(0)
	v_mfma_f32_16x16x32_bf16 v[120:123], v[124:127], v[236:239], v[120:123]
	s_nop 7
	v_cvt_pk_bf16_f32 v22, v240, v240
	v_cvt_pk_bf16_f32 v23, v241, v241
	v_cvt_pk_bf16_f32 v24, v242, v242
	v_cvt_pk_bf16_f32 v25, v243, v243
	v_cvt_pk_bf16_f32 v26, v244, v244
	v_cvt_pk_bf16_f32 v27, v245, v245
	v_cvt_pk_bf16_f32 v28, v246, v246
	v_cvt_pk_bf16_f32 v29, v247, v247
	v_cvt_pk_bf16_f32 v134, v248, v248
	v_cvt_pk_bf16_f32 v135, v249, v249
	v_cvt_pk_bf16_f32 v136, v250, v250
	v_cvt_pk_bf16_f32 v137, v251, v251
	v_cvt_pk_bf16_f32 v138, v120, v120
	v_cvt_pk_bf16_f32 v139, v121, v121
	v_cvt_pk_bf16_f32 v150, v122, v122
	v_cvt_pk_bf16_f32 v151, v123, v123
	global_store_short v17, v22, s[20:21]
	global_store_short v17, v23, s[20:21] offset:2048
	global_store_short v18, v24, s[20:21]
	global_store_short v18, v25, s[20:21] offset:2048
	global_store_short v17, v26, s[20:21] offset:32
	global_store_short v17, v27, s[20:21] offset:2080
	global_store_short v18, v28, s[20:21] offset:32
	global_store_short v18, v29, s[20:21] offset:2080
	global_store_short v17, v134, s[20:21] offset:64
	global_store_short v17, v135, s[20:21] offset:2112
	global_store_short v18, v136, s[20:21] offset:64
	global_store_short v18, v137, s[20:21] offset:2112
	global_store_short v17, v138, s[20:21] offset:96
	global_store_short v17, v139, s[20:21] offset:2144
	global_store_short v18, v150, s[20:21] offset:96
	global_store_short v18, v151, s[20:21] offset:2144
	s_add_u32 s3, s3, s6
	s_cmp_lt_u32 s3, 0x2000
	s_cbranch_scc1 .Lat_loop
	v_and_b32_e32 v10, 15, v0
	s_add_u32 s74, s0, 0xd8
	s_addc_u32 s75, s1, 0
	v_mov_b64_e32 v[2:3], s[74:75]
	s_mov_b64 s[64:65], exec
